# v43: v41 + GLA G3: the drain of the chunk-state and gate-input loads moved from right after the gate barrier to their first consumer (the state MFMA, ~500 instructions later)
# speedup vs baseline: 1.0041x; 1.0041x over previous
.LBB0_133:
	s_or_b64 exec, exec, s[0:1]
	v_lshl_add_u64 v[2:3], s[30:31], 0, v[96:97]
	v_mov_b64_e32 v[0:1], s[6:7]
	v_mad_u64_u32 v[4:5], s[0:1], v2, s26, v[0:1]
	v_mov_b32_e32 v2, v5
	v_mad_u64_u32 v[2:3], s[0:1], v3, s26, v[2:3]
	v_mov_b32_e32 v5, v2
	s_lshl_b32 s0, s5, 9
	s_mov_b32 s1, s4
	v_lshl_add_u64 v[2:3], v[4:5], 0, s[0:1]
	v_mov_b32_e32 v115, v193
	v_lshl_add_u64 v[2:3], v[2:3], 0, v[114:115]
	global_load_dwordx4 v[232:235], v[2:3], off offset:2048
	s_ashr_i32 s11, s10, 31
	v_or_b32_e32 v138, s30, v88
	s_mul_i32 s5, s31, 0x1a00
	v_or_b32_e32 v128, s30, v108
	v_mov_b32_e32 v117, v193
	s_mov_b64 s[80:81], 0x1000
	v_mov_b32_e32 v139, s31
	v_mov_b32_e32 v129, s31
	v_add_u32_e32 v113, 0xb000, v165
	v_lshl_add_u64 v[2:3], s[30:31], 0, v[98:99]
	v_mad_u64_u32 v[4:5], s[24:25], v2, s26, v[0:1]
	v_mov_b32_e32 v2, v5
	v_mad_u64_u32 v[2:3], s[24:25], v3, s26, v[2:3]
	v_mov_b32_e32 v5, v2
	v_lshl_add_u64 v[2:3], v[4:5], 0, s[0:1]
	v_lshl_add_u64 v[2:3], v[2:3], 0, v[114:115]
	global_load_dwordx4 v[236:239], v[2:3], off offset:2048
	v_lshl_add_u64 v[2:3], s[30:31], 0, v[100:101]
	v_mad_u64_u32 v[4:5], s[24:25], v2, s26, v[0:1]
	v_mov_b32_e32 v2, v5
	v_mad_u64_u32 v[2:3], s[24:25], v3, s26, v[2:3]
	v_mov_b32_e32 v5, v2
	v_lshl_add_u64 v[2:3], v[4:5], 0, s[0:1]
	v_lshl_add_u64 v[2:3], v[2:3], 0, v[114:115]
	global_load_dwordx4 v[240:243], v[2:3], off offset:2048
	v_lshl_add_u64 v[2:3], s[30:31], 0, v[102:103]
	v_mad_u64_u32 v[4:5], s[24:25], v2, s26, v[0:1]
	v_mov_b32_e32 v2, v5
	v_mad_u64_u32 v[2:3], s[24:25], v3, s26, v[2:3]
	v_mov_b32_e32 v5, v2
	v_lshl_add_u64 v[2:3], v[4:5], 0, s[0:1]
	v_lshl_add_u64 v[2:3], v[2:3], 0, v[114:115]
	global_load_dwordx4 v[182:185], v[2:3], off offset:2048
	s_lshl_b64 s[24:25], s[10:11], 16
	s_movk_i32 s11, 0x1000
	s_mov_b64 s[30:31], s[64:65]
	v_add_u32_e32 v115, 0xb000, v166
	s_waitcnt vmcnt(0)
	ds_write_b128 v16, v[216:219]
	ds_write_b128 v17, v[220:223]
	ds_write_b128 v18, v[224:227]
	ds_write_b128 v19, v[228:231]
	ds_write_b128 v151, v[232:235] offset:8192
	ds_write_b128 v152, v[236:239] offset:8192
	ds_write_b128 v153, v[240:243] offset:8192
	ds_write_b128 v154, v[182:185] offset:8192
	v_cmp_gt_u32_e32 vcc, 0x80, v195
	s_and_saveexec_b64 s[100:101], vcc
	ds_write_b128 v150, v[186:189]
	s_or_b64 exec, exec, s[100:101]
	v_readfirstlane_b32 s100, v89
	s_lshr_b32 s100, s100, 1
	s_and_b32 s100, s100, 0x60
	v_or_b32_e32 v222, s3, v88
	v_or_b32_e32 v222, s100, v222
	v_lshlrev_b32_e32 v220, 5, v222
	v_mov_b32_e32 v221, v193
	v_lshl_add_u64 v[220:221], v[106:107], 0, v[220:221]
	global_load_dwordx4 v[216:219], v[220:221], off
	v_readlane_b32 s100, v245, 38
	v_readlane_b32 s101, v245, 39
	v_lshlrev_b32_e32 v222, 2, v222
	s_nop 4
	global_load_dword v223, v222, s[100:101]
	v_lshl_add_u64 v[2:3], v[104:105], 0, s[24:25]
	v_readlane_b32 s24, v245, 58
	v_readlane_b32 s25, v245, 59
	s_nop 1
	v_lshl_add_u64 v[4:5], v[2:3], 0, s[24:25]
	v_readlane_b32 s24, v245, 46
	v_readlane_b32 s25, v245, 47
	global_load_dwordx4 v[60:63], v[4:5], off
	s_nop 0
	v_lshl_add_u64 v[4:5], v[2:3], 0, s[24:25]
	v_readlane_b32 s24, v245, 48
	v_readlane_b32 s25, v245, 49
	global_load_dwordx4 v[56:59], v[4:5], off
	s_nop 0
	v_lshl_add_u64 v[4:5], v[2:3], 0, s[24:25]
	v_readlane_b32 s24, v245, 50
	v_readlane_b32 s25, v245, 51
	global_load_dwordx4 v[52:55], v[4:5], off
	s_nop 0
	v_lshl_add_u64 v[4:5], v[2:3], 0, s[24:25]
	v_readlane_b32 s24, v245, 52
	v_readlane_b32 s25, v245, 53
	global_load_dwordx4 v[48:51], v[4:5], off
	s_nop 0
	v_lshl_add_u64 v[4:5], v[2:3], 0, s[24:25]
	v_readlane_b32 s24, v245, 54
	v_readlane_b32 s25, v245, 55
	global_load_dwordx4 v[44:47], v[4:5], off
	s_nop 0
	v_lshl_add_u64 v[4:5], v[2:3], 0, s[24:25]
	v_readlane_b32 s24, v245, 56
	v_readlane_b32 s25, v245, 57
	global_load_dwordx4 v[40:43], v[4:5], off
	s_nop 0
	v_lshl_add_u64 v[4:5], v[2:3], 0, s[24:25]
	v_readlane_b32 s24, v245, 60
	v_readlane_b32 s25, v245, 61
	global_load_dwordx4 v[36:39], v[4:5], off
	s_nop 0
	v_lshl_add_u64 v[2:3], v[2:3], 0, s[24:25]
	global_load_dwordx4 v[32:35], v[2:3], off
	v_mad_u64_u32 v[2:3], s[24:25], v138, s26, v[0:1]
	v_add_u32_e32 v3, s5, v3
	v_lshl_add_u64 v[2:3], v[2:3], 0, s[0:1]
	v_mad_u64_u32 v[0:1], s[24:25], v128, s26, v[0:1]
	v_lshl_add_u64 v[2:3], v[2:3], 0, s[8:9]
	v_add_u32_e32 v1, s5, v1
	v_lshl_add_u64 v[2:3], v[2:3], 0, v[116:117]
	v_lshl_add_u64 v[0:1], v[0:1], 0, s[0:1]
	v_lshl_add_u64 v[4:5], v[2:3], 0, s[80:81]
	v_add_co_u32_e32 v2, vcc, s11, v2
	v_lshl_add_u64 v[0:1], v[0:1], 0, s[8:9]
	v_readfirstlane_b32 s0, v89
	v_addc_co_u32_e32 v3, vcc, 0, v3, vcc
	v_lshl_add_u64 v[0:1], v[0:1], 0, v[116:117]
	s_ashr_i32 s1, s0, 3
	s_lshr_b32 s0, s0, 1
	global_load_dwordx2 v[136:137], v[2:3], off
	global_load_dwordx2 v[134:135], v[4:5], off offset:16
	global_load_dwordx2 v[132:133], v[4:5], off offset:32
	global_load_dwordx2 v[130:131], v[4:5], off offset:48
	v_lshl_add_u64 v[2:3], v[0:1], 0, s[80:81]
	v_add_co_u32_e32 v0, vcc, s11, v0
	s_and_b32 s11, s0, 0x60
	v_or_b32_e32 v4, s3, v88
	v_or_b32_e32 v16, s11, v4
	v_lshlrev_b32_e32 v4, 5, v16
	v_mov_b32_e32 v5, v193
	v_addc_co_u32_e32 v1, vcc, 0, v1, vcc
	v_lshl_add_u64 v[4:5], v[106:107], 0, v[4:5]
	global_load_dwordx2 v[126:127], v[0:1], off
	global_load_dwordx2 v[124:125], v[2:3], off offset:16
	global_load_dwordx2 v[122:123], v[2:3], off offset:32
	global_load_dwordx2 v[120:121], v[2:3], off offset:48
	s_waitcnt lgkmcnt(0)
	s_barrier
	s_and_b32 s5, s1, 0xffffffe0
	v_readlane_b32 s0, v245, 38
	v_lshlrev_b32_e32 v16, 2, v16
	v_readlane_b32 s1, v245, 39
	v_or_b32_e32 v0, s5, v88
	v_lshl_add_u32 v0, v0, 5, v145
	ds_read_b128 v[0:3], v0
	s_mov_b32 s3, 0xbfb8aa3b
	s_mov_b32 s24, 0x3f317217
	s_mov_b32 s25, 0x7f800000
	s_waitcnt vmcnt(16) lgkmcnt(0)
	v_mfma_f32_32x32x16_bf16 v[0:15], v[0:3], v[216:219], 0
	v_mov_b32_e32 v16, v223
	s_nop 10
	v_add_f32_e32 v0, v16, v0
	v_min_f32_e32 v17, 0, v0
	v_mul_f32_e64 v0, |v0|, s3
	v_exp_f32_e32 v0, v0
	v_add_f32_e32 v1, v16, v1
	v_add_f32_e32 v0, 1.0, v0
	v_cmp_gt_f32_e32 vcc, s83, v0
	s_nop 1
	v_cndmask_b32_e64 v18, 0, 32, vcc
	v_ldexp_f32 v0, v0, v18
	v_log_f32_e32 v0, v0
	s_nop 0
	v_mul_f32_e32 v18, 0x3f317217, v0
	v_fma_f32 v18, v0, s24, -v18
	v_fmac_f32_e32 v18, 0x3377d1cf, v0
	v_fmac_f32_e32 v18, 0x3f317217, v0
	v_cmp_lt_f32_e64 s[0:1], |v0|, s25
	s_nop 1
	v_cndmask_b32_e64 v0, v0, v18, s[0:1]
	v_cndmask_b32_e32 v18, 0, v211, vcc
	v_sub_f32_e32 v0, v0, v18
	v_min_f32_e32 v18, 0, v1
	v_mul_f32_e64 v1, |v1|, s3
	v_exp_f32_e32 v1, v1
	s_lshl_b32 s0, s5, 9
	s_lshl_b32 s1, s11, 2
	v_sub_f32_e32 v0, v17, v0
	v_add_f32_e32 v1, 1.0, v1
	v_cmp_gt_f32_e32 vcc, s83, v1
	s_or_b32 s0, s0, s1
	v_mul_f32_e32 v17, 0x3d800000, v0
	v_cndmask_b32_e64 v19, 0, 32, vcc
	v_ldexp_f32 v1, v1, v19
	v_log_f32_e32 v1, v1
	v_add_u32_e32 v0, s0, v146
	v_mul_f32_e32 v19, 0x3f317217, v1
	v_fma_f32 v19, v1, s24, -v19
	v_fmac_f32_e32 v19, 0x3377d1cf, v1
	v_fmac_f32_e32 v19, 0x3f317217, v1
	v_cmp_lt_f32_e64 s[0:1], |v1|, s25
	s_nop 1
	v_cndmask_b32_e64 v1, v1, v19, s[0:1]
	v_cndmask_b32_e32 v19, 0, v211, vcc
	v_sub_f32_e32 v1, v1, v19
	v_sub_f32_e32 v1, v18, v1
	v_mul_f32_e32 v1, 0x3d800000, v1
	ds_write2st64_b32 v0, v17, v1 offset0:176 offset1:178
	v_add_f32_e32 v1, v16, v2
	v_min_f32_e32 v2, 0, v1
	v_mul_f32_e64 v1, |v1|, s3
	v_exp_f32_e32 v1, v1
	s_nop 0
	v_add_f32_e32 v1, 1.0, v1
	v_cmp_gt_f32_e32 vcc, s83, v1
	s_nop 1
	v_cndmask_b32_e64 v17, 0, 32, vcc
	v_ldexp_f32 v1, v1, v17
	v_log_f32_e32 v1, v1
	s_nop 0
	v_mul_f32_e32 v17, 0x3f317217, v1
	v_fma_f32 v17, v1, s24, -v17
	v_fmac_f32_e32 v17, 0x3377d1cf, v1
	v_fmac_f32_e32 v17, 0x3f317217, v1
	v_cmp_lt_f32_e64 s[0:1], |v1|, s25
	s_nop 1
	v_cndmask_b32_e64 v1, v1, v17, s[0:1]
	v_cndmask_b32_e32 v17, 0, v211, vcc
	v_sub_f32_e32 v1, v1, v17
	v_sub_f32_e32 v1, v2, v1
	v_add_f32_e32 v2, v16, v3
	v_min_f32_e32 v3, 0, v2
	v_mul_f32_e64 v2, |v2|, s3
	v_exp_f32_e32 v2, v2
	v_mul_f32_e32 v1, 0x3d800000, v1
	v_add_f32_e32 v2, 1.0, v2
	v_cmp_gt_f32_e32 vcc, s83, v2
	s_nop 1
	v_cndmask_b32_e64 v17, 0, 32, vcc
	v_ldexp_f32 v2, v2, v17
	v_log_f32_e32 v2, v2
	s_nop 0
	v_mul_f32_e32 v17, 0x3f317217, v2
	v_fma_f32 v17, v2, s24, -v17
	v_fmac_f32_e32 v17, 0x3377d1cf, v2
	v_fmac_f32_e32 v17, 0x3f317217, v2
	v_cmp_lt_f32_e64 s[0:1], |v2|, s25
	s_nop 1
	v_cndmask_b32_e64 v2, v2, v17, s[0:1]
	v_cndmask_b32_e32 v17, 0, v211, vcc
	v_sub_f32_e32 v2, v2, v17
	v_sub_f32_e32 v2, v3, v2
	v_mul_f32_e32 v2, 0x3d800000, v2
	ds_write2st64_b32 v0, v1, v2 offset0:180 offset1:182
	v_add_f32_e32 v1, v16, v4
	v_min_f32_e32 v2, 0, v1
	v_mul_f32_e64 v1, |v1|, s3
	v_exp_f32_e32 v1, v1
	s_nop 0
	v_add_f32_e32 v1, 1.0, v1
	v_cmp_gt_f32_e32 vcc, s83, v1
	s_nop 1
	v_cndmask_b32_e64 v3, 0, 32, vcc
	v_ldexp_f32 v1, v1, v3
	v_log_f32_e32 v1, v1
	s_nop 0
	v_mul_f32_e32 v3, 0x3f317217, v1
	v_fma_f32 v3, v1, s24, -v3
	v_fmac_f32_e32 v3, 0x3377d1cf, v1
	v_fmac_f32_e32 v3, 0x3f317217, v1
	v_cmp_lt_f32_e64 s[0:1], |v1|, s25
	s_nop 1
	v_cndmask_b32_e64 v1, v1, v3, s[0:1]
	v_cndmask_b32_e32 v3, 0, v211, vcc
	v_sub_f32_e32 v1, v1, v3
	v_sub_f32_e32 v1, v2, v1
	v_add_f32_e32 v2, v16, v5
	v_min_f32_e32 v3, 0, v2
	v_mul_f32_e64 v2, |v2|, s3
	v_exp_f32_e32 v2, v2
	v_mul_f32_e32 v1, 0x3d800000, v1
	v_add_f32_e32 v2, 1.0, v2
	v_cmp_gt_f32_e32 vcc, s83, v2
	s_nop 1
	v_cndmask_b32_e64 v4, 0, 32, vcc
	v_ldexp_f32 v2, v2, v4
	v_log_f32_e32 v2, v2
	s_nop 0
	v_mul_f32_e32 v4, 0x3f317217, v2
	v_fma_f32 v4, v2, s24, -v4
	v_fmac_f32_e32 v4, 0x3377d1cf, v2
	v_fmac_f32_e32 v4, 0x3f317217, v2
	v_cmp_lt_f32_e64 s[0:1], |v2|, s25
	s_nop 1
	v_cndmask_b32_e64 v2, v2, v4, s[0:1]
	v_cndmask_b32_e32 v4, 0, v211, vcc
	v_sub_f32_e32 v2, v2, v4
	v_sub_f32_e32 v2, v3, v2
	v_mul_f32_e32 v2, 0x3d800000, v2
	ds_write2st64_b32 v0, v1, v2 offset0:192 offset1:194
	v_add_f32_e32 v1, v16, v6
	v_min_f32_e32 v2, 0, v1
	v_mul_f32_e64 v1, |v1|, s3
	v_exp_f32_e32 v1, v1
	s_nop 0
	v_add_f32_e32 v1, 1.0, v1
	v_cmp_gt_f32_e32 vcc, s83, v1
	s_nop 1
	v_cndmask_b32_e64 v3, 0, 32, vcc
	v_ldexp_f32 v1, v1, v3
	v_log_f32_e32 v1, v1
	s_nop 0
	v_mul_f32_e32 v3, 0x3f317217, v1
	v_fma_f32 v3, v1, s24, -v3
	v_fmac_f32_e32 v3, 0x3377d1cf, v1
	v_fmac_f32_e32 v3, 0x3f317217, v1
	v_cmp_lt_f32_e64 s[0:1], |v1|, s25
	s_nop 1
	v_cndmask_b32_e64 v1, v1, v3, s[0:1]
	v_cndmask_b32_e32 v3, 0, v211, vcc
	v_sub_f32_e32 v1, v1, v3
	v_sub_f32_e32 v1, v2, v1
	v_add_f32_e32 v2, v16, v7
	v_min_f32_e32 v3, 0, v2
	v_mul_f32_e64 v2, |v2|, s3
	v_exp_f32_e32 v2, v2
	v_mul_f32_e32 v1, 0x3d800000, v1
	v_add_f32_e32 v2, 1.0, v2
	v_cmp_gt_f32_e32 vcc, s83, v2
	s_nop 1
	v_cndmask_b32_e64 v4, 0, 32, vcc
	v_ldexp_f32 v2, v2, v4
	v_log_f32_e32 v2, v2
	s_nop 0
	v_mul_f32_e32 v4, 0x3f317217, v2
	v_fma_f32 v4, v2, s24, -v4
	v_fmac_f32_e32 v4, 0x3377d1cf, v2
	v_fmac_f32_e32 v4, 0x3f317217, v2
	v_cmp_lt_f32_e64 s[0:1], |v2|, s25
	s_nop 1
	v_cndmask_b32_e64 v2, v2, v4, s[0:1]
	v_cndmask_b32_e32 v4, 0, v211, vcc
	v_sub_f32_e32 v2, v2, v4
	v_sub_f32_e32 v2, v3, v2
	v_mul_f32_e32 v2, 0x3d800000, v2
	ds_write2st64_b32 v0, v1, v2 offset0:196 offset1:198
	v_add_f32_e32 v1, v16, v8
	v_min_f32_e32 v2, 0, v1
	v_mul_f32_e64 v1, |v1|, s3
	v_exp_f32_e32 v1, v1
	s_nop 0
	v_add_f32_e32 v1, 1.0, v1
	v_cmp_gt_f32_e32 vcc, s83, v1
	s_nop 1
	v_cndmask_b32_e64 v3, 0, 32, vcc
	v_ldexp_f32 v1, v1, v3
	v_log_f32_e32 v1, v1
	s_nop 0
	v_mul_f32_e32 v3, 0x3f317217, v1
	v_fma_f32 v3, v1, s24, -v3
	v_fmac_f32_e32 v3, 0x3377d1cf, v1
	v_fmac_f32_e32 v3, 0x3f317217, v1
	v_cmp_lt_f32_e64 s[0:1], |v1|, s25
	s_nop 1
	v_cndmask_b32_e64 v1, v1, v3, s[0:1]
	v_cndmask_b32_e32 v3, 0, v211, vcc
	v_sub_f32_e32 v1, v1, v3
	v_sub_f32_e32 v1, v2, v1
	v_add_f32_e32 v2, v16, v9
	v_min_f32_e32 v3, 0, v2
	v_mul_f32_e64 v2, |v2|, s3
	v_exp_f32_e32 v2, v2
	v_mul_f32_e32 v1, 0x3d800000, v1
	v_add_f32_e32 v2, 1.0, v2
	v_cmp_gt_f32_e32 vcc, s83, v2
	s_nop 1
	v_cndmask_b32_e64 v4, 0, 32, vcc
	v_ldexp_f32 v2, v2, v4
	v_log_f32_e32 v2, v2
	s_nop 0
	v_mul_f32_e32 v4, 0x3f317217, v2
	v_fma_f32 v4, v2, s24, -v4
	v_fmac_f32_e32 v4, 0x3377d1cf, v2
	v_fmac_f32_e32 v4, 0x3f317217, v2
	v_cmp_lt_f32_e64 s[0:1], |v2|, s25
	s_nop 1
	v_cndmask_b32_e64 v2, v2, v4, s[0:1]
	v_cndmask_b32_e32 v4, 0, v211, vcc
	v_sub_f32_e32 v2, v2, v4
	v_sub_f32_e32 v2, v3, v2
	v_mul_f32_e32 v2, 0x3d800000, v2
	ds_write2st64_b32 v0, v1, v2 offset0:208 offset1:210
	v_add_f32_e32 v1, v16, v10
	v_min_f32_e32 v2, 0, v1
	v_mul_f32_e64 v1, |v1|, s3
	v_exp_f32_e32 v1, v1
	s_nop 0
	v_add_f32_e32 v1, 1.0, v1
	v_cmp_gt_f32_e32 vcc, s83, v1
	s_nop 1
	v_cndmask_b32_e64 v3, 0, 32, vcc
	v_ldexp_f32 v1, v1, v3
	v_log_f32_e32 v1, v1
	s_nop 0
	v_mul_f32_e32 v3, 0x3f317217, v1
	v_fma_f32 v3, v1, s24, -v3
	v_fmac_f32_e32 v3, 0x3377d1cf, v1
	v_fmac_f32_e32 v3, 0x3f317217, v1
	v_cmp_lt_f32_e64 s[0:1], |v1|, s25
	s_nop 1
	v_cndmask_b32_e64 v1, v1, v3, s[0:1]
	v_cndmask_b32_e32 v3, 0, v211, vcc
	v_sub_f32_e32 v1, v1, v3
	v_sub_f32_e32 v1, v2, v1
	v_add_f32_e32 v2, v16, v11
	v_min_f32_e32 v3, 0, v2
	v_mul_f32_e64 v2, |v2|, s3
	v_exp_f32_e32 v2, v2
	v_mul_f32_e32 v1, 0x3d800000, v1
	v_add_f32_e32 v2, 1.0, v2
	v_cmp_gt_f32_e32 vcc, s83, v2
	s_nop 1
	v_cndmask_b32_e64 v4, 0, 32, vcc
	v_ldexp_f32 v2, v2, v4
	v_log_f32_e32 v2, v2
	s_nop 0
	v_mul_f32_e32 v4, 0x3f317217, v2
	v_fma_f32 v4, v2, s24, -v4
	v_fmac_f32_e32 v4, 0x3377d1cf, v2
	v_fmac_f32_e32 v4, 0x3f317217, v2
	v_cmp_lt_f32_e64 s[0:1], |v2|, s25
	s_nop 1
	v_cndmask_b32_e64 v2, v2, v4, s[0:1]
	v_cndmask_b32_e32 v4, 0, v211, vcc
	v_sub_f32_e32 v2, v2, v4
	v_sub_f32_e32 v2, v3, v2
	v_mul_f32_e32 v2, 0x3d800000, v2
	ds_write2st64_b32 v0, v1, v2 offset0:212 offset1:214
	v_add_f32_e32 v1, v16, v12
	v_min_f32_e32 v2, 0, v1
	v_mul_f32_e64 v1, |v1|, s3
	v_exp_f32_e32 v1, v1
	s_nop 0
	v_add_f32_e32 v1, 1.0, v1
	v_cmp_gt_f32_e32 vcc, s83, v1
	s_nop 1
	v_cndmask_b32_e64 v3, 0, 32, vcc
	v_ldexp_f32 v1, v1, v3
	v_log_f32_e32 v1, v1
	s_nop 0
	v_mul_f32_e32 v3, 0x3f317217, v1
	v_fma_f32 v3, v1, s24, -v3
	v_fmac_f32_e32 v3, 0x3377d1cf, v1
	v_fmac_f32_e32 v3, 0x3f317217, v1
	v_cmp_lt_f32_e64 s[0:1], |v1|, s25
	s_nop 1
	v_cndmask_b32_e64 v1, v1, v3, s[0:1]
	v_cndmask_b32_e32 v3, 0, v211, vcc
	v_sub_f32_e32 v1, v1, v3
	v_sub_f32_e32 v1, v2, v1
	v_add_f32_e32 v2, v16, v13
	v_min_f32_e32 v3, 0, v2
	v_mul_f32_e64 v2, |v2|, s3
	v_exp_f32_e32 v2, v2
	v_mul_f32_e32 v1, 0x3d800000, v1
	v_add_f32_e32 v2, 1.0, v2
	v_cmp_gt_f32_e32 vcc, s83, v2
	s_nop 1
	v_cndmask_b32_e64 v4, 0, 32, vcc
	v_ldexp_f32 v2, v2, v4
	v_log_f32_e32 v2, v2
	s_nop 0
	v_mul_f32_e32 v4, 0x3f317217, v2
	v_fma_f32 v4, v2, s24, -v4
	v_fmac_f32_e32 v4, 0x3377d1cf, v2
	v_fmac_f32_e32 v4, 0x3f317217, v2
	v_cmp_lt_f32_e64 s[0:1], |v2|, s25
	s_nop 1
	v_cndmask_b32_e64 v2, v2, v4, s[0:1]
	v_cndmask_b32_e32 v4, 0, v211, vcc
	v_sub_f32_e32 v2, v2, v4
	v_sub_f32_e32 v2, v3, v2
	v_mul_f32_e32 v2, 0x3d800000, v2
	ds_write2st64_b32 v0, v1, v2 offset0:224 offset1:226
	v_add_f32_e32 v1, v16, v14
	v_min_f32_e32 v2, 0, v1
	v_mul_f32_e64 v1, |v1|, s3
	v_exp_f32_e32 v1, v1
	s_nop 0
	v_add_f32_e32 v1, 1.0, v1
	v_cmp_gt_f32_e32 vcc, s83, v1
	s_nop 1
	v_cndmask_b32_e64 v3, 0, 32, vcc
	v_ldexp_f32 v1, v1, v3
	v_log_f32_e32 v1, v1
	s_nop 0
	v_mul_f32_e32 v3, 0x3f317217, v1
	v_fma_f32 v3, v1, s24, -v3
	v_fmac_f32_e32 v3, 0x3377d1cf, v1
	v_fmac_f32_e32 v3, 0x3f317217, v1
	v_cmp_lt_f32_e64 s[0:1], |v1|, s25
	s_nop 1
	v_cndmask_b32_e64 v1, v1, v3, s[0:1]
	v_cndmask_b32_e32 v3, 0, v211, vcc
	v_sub_f32_e32 v1, v1, v3
	v_sub_f32_e32 v1, v2, v1
	v_add_f32_e32 v2, v16, v15
	v_min_f32_e32 v3, 0, v2
	v_mul_f32_e64 v2, |v2|, s3
	v_exp_f32_e32 v2, v2
	v_mul_f32_e32 v1, 0x3d800000, v1
	v_add_f32_e32 v2, 1.0, v2
	v_cmp_gt_f32_e32 vcc, s83, v2
	s_nop 1
	v_cndmask_b32_e64 v4, 0, 32, vcc
	v_ldexp_f32 v2, v2, v4
	v_log_f32_e32 v2, v2
	s_nop 0
	v_mul_f32_e32 v4, 0x3f317217, v2
	v_fma_f32 v4, v2, s24, -v4
	v_fmac_f32_e32 v4, 0x3377d1cf, v2
	v_fmac_f32_e32 v4, 0x3f317217, v2
	v_cmp_lt_f32_e64 s[0:1], |v2|, s25
	v_readlane_b32 s24, v244, 0
	v_readlane_b32 s25, v244, 1
	v_cndmask_b32_e64 v2, v2, v4, s[0:1]
	v_cndmask_b32_e32 v4, 0, v211, vcc
	v_sub_f32_e32 v2, v2, v4
	v_sub_f32_e32 v2, v3, v2
	v_mul_f32_e32 v2, 0x3d800000, v2
	ds_write2st64_b32 v0, v1, v2 offset0:228 offset1:230
	s_waitcnt lgkmcnt(0)
	s_barrier
	ds_read2st64_b32 v[0:1], v155 offset0:176 offset1:178
	v_readlane_b32 s0, v245, 36
	v_readlane_b32 s1, v245, 37
	s_waitcnt lgkmcnt(0)
	v_add_f32_e32 v2, 0, v0
	v_add_f32_e32 v3, v2, v1
	ds_read2st64_b32 v[0:1], v155 offset0:180 offset1:182
	s_waitcnt lgkmcnt(0)
	v_add_f32_e32 v4, v3, v0
	v_add_f32_e32 v5, v4, v1
	ds_read2st64_b32 v[0:1], v155 offset0:184 offset1:186
	s_waitcnt lgkmcnt(0)
	v_add_f32_e32 v6, v5, v0
	v_add_f32_e32 v7, v6, v1
	ds_read2st64_b32 v[0:1], v155 offset0:188 offset1:190
	s_waitcnt lgkmcnt(0)
	v_add_f32_e32 v8, v7, v0
	v_add_f32_e32 v9, v8, v1
	ds_read2st64_b32 v[0:1], v155 offset0:192 offset1:194
	s_waitcnt lgkmcnt(0)
	v_add_f32_e32 v10, v9, v0
	v_add_f32_e32 v11, v10, v1
	ds_read2st64_b32 v[0:1], v155 offset0:196 offset1:198
	s_waitcnt lgkmcnt(0)
	v_add_f32_e32 v12, v11, v0
	v_add_f32_e32 v13, v12, v1
	ds_read2st64_b32 v[0:1], v155 offset0:200 offset1:202
	s_waitcnt lgkmcnt(0)
	v_add_f32_e32 v14, v13, v0
	v_add_f32_e32 v15, v14, v1
	ds_read2st64_b32 v[0:1], v155 offset0:204 offset1:206
	s_waitcnt lgkmcnt(0)
	v_add_f32_e32 v16, v15, v0
	v_add_f32_e32 v17, v16, v1
	ds_write_b32 v156, v17 offset:4096
	s_waitcnt lgkmcnt(0)
	s_barrier
	ds_read2st64_b32 v[0:1], v140 offset0:16 offset1:18
	s_waitcnt lgkmcnt(0)
	v_add_f32_e32 v0, 0, v0
	v_cndmask_b32_e64 v0, 0, v0, s[0:1]
	v_readlane_b32 s0, v245, 31
	v_add_f32_e32 v1, v1, v0
	v_readlane_b32 s1, v245, 32
	s_nop 1
	v_cndmask_b32_e64 v18, v0, v1, s[0:1]
	ds_read2st64_b32 v[0:1], v140 offset0:20 offset1:22
	v_readlane_b32 s0, v245, 40
	v_readlane_b32 s1, v245, 41
	s_waitcnt lgkmcnt(0)
	v_add_f32_e32 v0, v0, v18
	v_cndmask_b32_e64 v0, v18, v0, s[0:1]
	v_readlane_b32 s0, v245, 42
	v_add_f32_e32 v1, v1, v0
	v_readlane_b32 s1, v245, 43
	s_nop 1
	v_cndmask_b32_e64 v0, v0, v1, s[0:1]
	v_add_f32_e32 v23, v8, v0
	v_add_f32_e32 v8, v10, v0
	ds_read_u16 v10, v157
	v_add_f32_e32 v1, v2, v0
	v_add_f32_e32 v22, v7, v0
	v_add_f32_e32 v7, v11, v0
	v_mul_f32_e32 v11, 0x3fb8aa3b, v1
	v_exp_f32_e32 v11, v11
	s_waitcnt lgkmcnt(0)
	v_lshlrev_b32_e32 v10, 16, v10
	v_mul_f32_e32 v10, 0x3db504f3, v10
	v_mul_f32_e32 v1, 0xbfb8aa3b, v1
	v_mul_f32_e32 v10, v10, v11
	ds_read_u16 v11, v158
	v_exp_f32_e32 v1, v1
	s_movk_i32 s0, 0x7fff
	v_add_f32_e32 v18, v3, v0
	v_add_f32_e32 v21, v6, v0
	s_waitcnt lgkmcnt(0)
	v_lshlrev_b32_e32 v11, 16, v11
	v_mul_f32_e32 v11, v1, v11
	v_bfe_u32 v1, v10, 16, 1
	v_add3_u32 v10, v10, v1, s0
	v_add_u32_e32 v1, v147, v149
	ds_write_b16_d16_hi v1, v10 offset:45056
	v_bfe_u32 v10, v11, 16, 1
	v_add3_u32 v10, v11, v10, s0
	ds_write_b16_d16_hi v1, v10 offset:62464
	ds_read_u16 v10, v157 offset:256
	v_mul_f32_e32 v11, 0x3fb8aa3b, v18
	v_exp_f32_e32 v11, v11
	v_add_f32_e32 v6, v12, v0
	v_mul_f32_e32 v12, 0xbfb8aa3b, v18
	s_waitcnt lgkmcnt(0)
	v_lshlrev_b32_e32 v10, 16, v10
	v_mul_f32_e32 v10, 0x3db504f3, v10
	v_mul_f32_e32 v10, v11, v10
	ds_read_u16 v11, v158 offset:256
	v_exp_f32_e32 v12, v12
	v_add_f32_e32 v19, v4, v0
	v_add_f32_e32 v20, v5, v0
	v_add_f32_e32 v9, v9, v0
	s_waitcnt lgkmcnt(0)
	v_lshlrev_b32_e32 v11, 16, v11
	v_mul_f32_e32 v11, v12, v11
	v_bfe_u32 v12, v10, 16, 1
	v_add3_u32 v10, v10, v12, s0
	ds_write_b16_d16_hi v1, v10 offset:45328
	v_bfe_u32 v10, v11, 16, 1
	v_add3_u32 v10, v11, v10, s0
	ds_write_b16_d16_hi v1, v10 offset:62736
	ds_read_u16 v10, v157 offset:512
	v_mul_f32_e32 v11, 0x3fb8aa3b, v19
	v_exp_f32_e32 v11, v11
	v_mul_f32_e32 v12, 0xbfb8aa3b, v19
	v_exp_f32_e32 v12, v12
	s_waitcnt lgkmcnt(0)
	v_lshlrev_b32_e32 v10, 16, v10
	v_mul_f32_e32 v10, 0x3db504f3, v10
	v_mul_f32_e32 v10, v11, v10
	ds_read_u16 v11, v158 offset:512
	v_add_f32_e32 v5, v13, v0
	v_add_f32_e32 v4, v14, v0
	v_add_f32_e32 v3, v15, v0
	v_add_f32_e32 v2, v16, v0
	s_waitcnt lgkmcnt(0)
	v_lshlrev_b32_e32 v11, 16, v11
	v_mul_f32_e32 v11, v12, v11
	v_bfe_u32 v12, v10, 16, 1
	v_add3_u32 v10, v10, v12, s0
	ds_write_b16_d16_hi v1, v10 offset:45600
	v_bfe_u32 v10, v11, 16, 1
	v_add3_u32 v10, v11, v10, s0
	ds_write_b16_d16_hi v1, v10 offset:63008
	ds_read_u16 v10, v157 offset:768
	v_mul_f32_e32 v11, 0x3fb8aa3b, v20
	v_exp_f32_e32 v11, v11
	v_mul_f32_e32 v12, 0xbfb8aa3b, v20
	v_exp_f32_e32 v12, v12
	s_waitcnt lgkmcnt(0)
	v_lshlrev_b32_e32 v10, 16, v10
	v_mul_f32_e32 v10, 0x3db504f3, v10
	v_mul_f32_e32 v10, v11, v10
	ds_read_u16 v11, v158 offset:768
	v_add_f32_e32 v0, v17, v0
	s_waitcnt lgkmcnt(0)
	v_lshlrev_b32_e32 v11, 16, v11
	v_mul_f32_e32 v11, v12, v11
	v_bfe_u32 v12, v10, 16, 1
	v_add3_u32 v10, v10, v12, s0
	ds_write_b16_d16_hi v1, v10 offset:45872
	v_bfe_u32 v10, v11, 16, 1
	v_add3_u32 v10, v11, v10, s0
	ds_write_b16_d16_hi v1, v10 offset:63280
	ds_read_u16 v10, v157 offset:1024
	v_mul_f32_e32 v11, 0x3fb8aa3b, v21
	v_exp_f32_e32 v11, v11
	v_mul_f32_e32 v12, 0xbfb8aa3b, v21
	v_exp_f32_e32 v12, v12
	s_waitcnt lgkmcnt(0)
	v_lshlrev_b32_e32 v10, 16, v10
	v_mul_f32_e32 v10, 0x3db504f3, v10
	v_mul_f32_e32 v10, v11, v10
	ds_read_u16 v11, v158 offset:1024
	s_waitcnt lgkmcnt(0)
	v_lshlrev_b32_e32 v11, 16, v11
	v_mul_f32_e32 v11, v12, v11
	v_bfe_u32 v12, v10, 16, 1
	v_add3_u32 v10, v10, v12, s0
	ds_write_b16_d16_hi v1, v10 offset:46144
	v_bfe_u32 v10, v11, 16, 1
	v_add3_u32 v10, v11, v10, s0
	ds_write_b16_d16_hi v1, v10 offset:63552
	ds_read_u16 v10, v157 offset:1280
	v_mul_f32_e32 v11, 0x3fb8aa3b, v22
	v_exp_f32_e32 v11, v11
	v_mul_f32_e32 v12, 0xbfb8aa3b, v22
	v_exp_f32_e32 v12, v12
	s_waitcnt lgkmcnt(0)
	v_lshlrev_b32_e32 v10, 16, v10
	v_mul_f32_e32 v10, 0x3db504f3, v10
	v_mul_f32_e32 v10, v11, v10
	ds_read_u16 v11, v158 offset:1280
	s_waitcnt lgkmcnt(0)
	v_lshlrev_b32_e32 v11, 16, v11
	v_mul_f32_e32 v11, v12, v11
	v_bfe_u32 v12, v10, 16, 1
	v_add3_u32 v10, v10, v12, s0
	ds_write_b16_d16_hi v1, v10 offset:46416
	v_bfe_u32 v10, v11, 16, 1
	v_add3_u32 v10, v11, v10, s0
	ds_write_b16_d16_hi v1, v10 offset:63824
	ds_read_u16 v10, v157 offset:1536
	v_mul_f32_e32 v11, 0x3fb8aa3b, v23
	v_exp_f32_e32 v11, v11
	v_mul_f32_e32 v12, 0xbfb8aa3b, v23
	v_exp_f32_e32 v12, v12
	s_waitcnt lgkmcnt(0)
	v_lshlrev_b32_e32 v10, 16, v10
	v_mul_f32_e32 v10, 0x3db504f3, v10
	v_mul_f32_e32 v10, v11, v10
	ds_read_u16 v11, v158 offset:1536
	s_waitcnt lgkmcnt(0)
	v_lshlrev_b32_e32 v11, 16, v11
	v_mul_f32_e32 v11, v12, v11
	v_bfe_u32 v12, v10, 16, 1
	v_add3_u32 v10, v10, v12, s0
	ds_write_b16_d16_hi v1, v10 offset:46688
	v_bfe_u32 v10, v11, 16, 1
	v_add3_u32 v10, v11, v10, s0
	ds_write_b16_d16_hi v1, v10 offset:64096
	ds_read_u16 v10, v157 offset:1792
	v_mul_f32_e32 v11, 0x3fb8aa3b, v9
	v_exp_f32_e32 v11, v11
	v_mul_f32_e32 v9, 0xbfb8aa3b, v9
	v_exp_f32_e32 v9, v9
	s_waitcnt lgkmcnt(0)
	v_lshlrev_b32_e32 v10, 16, v10
	v_mul_f32_e32 v10, 0x3db504f3, v10
	v_mul_f32_e32 v10, v11, v10
	ds_read_u16 v11, v158 offset:1792
	s_waitcnt lgkmcnt(0)
	v_lshlrev_b32_e32 v11, 16, v11
	v_mul_f32_e32 v9, v9, v11
	v_bfe_u32 v11, v10, 16, 1
	v_add3_u32 v10, v10, v11, s0
	ds_write_b16_d16_hi v1, v10 offset:46960
	v_bfe_u32 v10, v9, 16, 1
	v_add3_u32 v9, v9, v10, s0
	ds_write_b16_d16_hi v1, v9 offset:64368
	ds_read_u16 v9, v157 offset:2048
	v_mul_f32_e32 v10, 0x3fb8aa3b, v8
	v_exp_f32_e32 v10, v10
	v_mul_f32_e32 v8, 0xbfb8aa3b, v8
	v_exp_f32_e32 v8, v8
	s_waitcnt lgkmcnt(0)
	v_lshlrev_b32_e32 v9, 16, v9
	v_mul_f32_e32 v9, 0x3db504f3, v9
	v_mul_f32_e32 v9, v10, v9
	ds_read_u16 v10, v158 offset:2048
	s_waitcnt lgkmcnt(0)
	v_lshlrev_b32_e32 v10, 16, v10
	v_mul_f32_e32 v8, v8, v10
	v_bfe_u32 v10, v9, 16, 1
	v_add3_u32 v9, v9, v10, s0
	ds_write_b16_d16_hi v1, v9 offset:47232
	v_bfe_u32 v9, v8, 16, 1
	v_add3_u32 v8, v8, v9, s0
	ds_write_b16_d16_hi v1, v8 offset:64640
	ds_read_u16 v8, v157 offset:2304
	v_mul_f32_e32 v9, 0x3fb8aa3b, v7
	v_exp_f32_e32 v9, v9
	v_mul_f32_e32 v7, 0xbfb8aa3b, v7
	v_exp_f32_e32 v7, v7
	s_waitcnt lgkmcnt(0)
	v_lshlrev_b32_e32 v8, 16, v8
	v_mul_f32_e32 v8, 0x3db504f3, v8
	v_mul_f32_e32 v8, v9, v8
	ds_read_u16 v9, v158 offset:2304
	s_waitcnt lgkmcnt(0)
	v_lshlrev_b32_e32 v9, 16, v9
	v_mul_f32_e32 v7, v7, v9
	v_bfe_u32 v9, v8, 16, 1
	v_add3_u32 v8, v8, v9, s0
	ds_write_b16_d16_hi v1, v8 offset:47504
	v_bfe_u32 v8, v7, 16, 1
	v_add3_u32 v7, v7, v8, s0
	ds_write_b16_d16_hi v1, v7 offset:64912
	ds_read_u16 v7, v157 offset:2560
	v_mul_f32_e32 v8, 0x3fb8aa3b, v6
	v_exp_f32_e32 v8, v8
	v_mul_f32_e32 v6, 0xbfb8aa3b, v6
	v_exp_f32_e32 v6, v6
	s_waitcnt lgkmcnt(0)
	v_lshlrev_b32_e32 v7, 16, v7
	v_mul_f32_e32 v7, 0x3db504f3, v7
	v_mul_f32_e32 v7, v8, v7
	ds_read_u16 v8, v158 offset:2560
	s_waitcnt lgkmcnt(0)
	v_lshlrev_b32_e32 v8, 16, v8
	v_mul_f32_e32 v6, v6, v8
	v_bfe_u32 v8, v7, 16, 1
	v_add3_u32 v7, v7, v8, s0
	ds_write_b16_d16_hi v1, v7 offset:47776
	v_bfe_u32 v7, v6, 16, 1
	v_add3_u32 v6, v6, v7, s0
	ds_write_b16_d16_hi v1, v6 offset:65184
	ds_read_u16 v6, v157 offset:2816
	v_mul_f32_e32 v7, 0x3fb8aa3b, v5
	v_exp_f32_e32 v7, v7
	v_mul_f32_e32 v5, 0xbfb8aa3b, v5
	v_exp_f32_e32 v5, v5
	s_waitcnt lgkmcnt(0)
	v_lshlrev_b32_e32 v6, 16, v6
	v_mul_f32_e32 v6, 0x3db504f3, v6
	v_mul_f32_e32 v6, v7, v6
	ds_read_u16 v7, v158 offset:2816
	s_waitcnt lgkmcnt(0)
	v_lshlrev_b32_e32 v7, 16, v7
	v_mul_f32_e32 v5, v5, v7
	v_bfe_u32 v7, v6, 16, 1
	v_add3_u32 v6, v6, v7, s0
	ds_write_b16_d16_hi v1, v6 offset:48048
	v_bfe_u32 v6, v5, 16, 1
	v_add3_u32 v5, v5, v6, s0
	ds_write_b16_d16_hi v1, v5 offset:65456
	ds_read_u16 v5, v157 offset:3072
	v_mul_f32_e32 v6, 0x3fb8aa3b, v4
	v_exp_f32_e32 v6, v6
	v_mul_f32_e32 v4, 0xbfb8aa3b, v4
	v_exp_f32_e32 v4, v4
	s_waitcnt lgkmcnt(0)
	v_lshlrev_b32_e32 v5, 16, v5
	v_mul_f32_e32 v5, 0x3db504f3, v5
	v_mul_f32_e32 v5, v6, v5
	ds_read_u16 v6, v158 offset:3072
	s_waitcnt lgkmcnt(0)
	v_lshlrev_b32_e32 v6, 16, v6
	v_mul_f32_e32 v4, v4, v6
	v_bfe_u32 v6, v5, 16, 1
	v_add3_u32 v5, v5, v6, s0
	ds_write_b16_d16_hi v1, v5 offset:48320
	v_bfe_u32 v5, v4, 16, 1
	v_add3_u32 v4, v4, v5, s0
	ds_write_b16_d16_hi v159, v4 offset:62464
	ds_read_u16 v4, v157 offset:3328
	v_mul_f32_e32 v5, 0x3fb8aa3b, v3
	v_exp_f32_e32 v5, v5
	v_mul_f32_e32 v3, 0xbfb8aa3b, v3
	v_exp_f32_e32 v3, v3
	s_waitcnt lgkmcnt(0)
	v_lshlrev_b32_e32 v4, 16, v4
	v_mul_f32_e32 v4, 0x3db504f3, v4
	v_mul_f32_e32 v4, v5, v4
	ds_read_u16 v5, v158 offset:3328
	s_waitcnt lgkmcnt(0)
	v_lshlrev_b32_e32 v5, 16, v5
	v_mul_f32_e32 v3, v3, v5
	v_bfe_u32 v5, v4, 16, 1
	v_add3_u32 v4, v4, v5, s0
	ds_write_b16_d16_hi v1, v4 offset:48592
	v_bfe_u32 v4, v3, 16, 1
	v_add3_u32 v3, v3, v4, s0
	ds_write_b16_d16_hi v160, v3 offset:62464
	ds_read_u16 v3, v157 offset:3584
	v_mul_f32_e32 v4, 0x3fb8aa3b, v2
	v_exp_f32_e32 v4, v4
	v_mul_f32_e32 v2, 0xbfb8aa3b, v2
	v_exp_f32_e32 v2, v2
	s_waitcnt lgkmcnt(0)
	v_lshlrev_b32_e32 v3, 16, v3
	v_mul_f32_e32 v3, 0x3db504f3, v3
	v_mul_f32_e32 v3, v4, v3
	ds_read_u16 v4, v158 offset:3584
	s_waitcnt lgkmcnt(0)
	v_lshlrev_b32_e32 v4, 16, v4
	v_mul_f32_e32 v2, v2, v4
	v_bfe_u32 v4, v3, 16, 1
	v_add3_u32 v3, v3, v4, s0
	ds_write_b16_d16_hi v1, v3 offset:48864
	v_bfe_u32 v3, v2, 16, 1
	v_add3_u32 v2, v2, v3, s0
	ds_write_b16_d16_hi v161, v2 offset:62464
	ds_read_u16 v2, v157 offset:3840
	v_mul_f32_e32 v3, 0x3fb8aa3b, v0
	v_exp_f32_e32 v3, v3
	v_mul_f32_e32 v0, 0xbfb8aa3b, v0
	v_exp_f32_e32 v0, v0
	s_waitcnt lgkmcnt(0)
	v_lshlrev_b32_e32 v2, 16, v2
	v_mul_f32_e32 v2, 0x3db504f3, v2
	v_mul_f32_e32 v2, v3, v2
	ds_read_u16 v3, v158 offset:3840
	s_waitcnt lgkmcnt(0)
	v_lshlrev_b32_e32 v3, 16, v3
	v_mul_f32_e32 v0, v0, v3
	v_bfe_u32 v3, v2, 16, 1
	v_add3_u32 v2, v2, v3, s0
	ds_write_b16_d16_hi v1, v2 offset:49136
	v_bfe_u32 v1, v0, 16, 1
	v_add3_u32 v0, v0, v1, s0
	ds_write_b16_d16_hi v162, v0 offset:62464
	s_waitcnt lgkmcnt(0)
	s_barrier
	ds_read_b128 v[16:19], v163 offset:62464
	ds_read_b128 v[0:3], v163 offset:45056
	ds_read_b128 v[20:23], v163 offset:45088
	ds_read_b128 v[24:27], v163 offset:62496
	s_waitcnt lgkmcnt(2)
	v_mfma_f32_32x32x16_bf16 v[0:15], v[16:19], v[0:3], 0
	v_readlane_b32 s0, v245, 62
	v_readlane_b32 s1, v245, 63
	s_waitcnt lgkmcnt(0)
	v_mfma_f32_32x32x16_bf16 v[0:15], v[24:27], v[20:23], v[0:15]
	ds_read_b128 v[20:23], v163 offset:62528
	ds_read_b128 v[28:31], v163 offset:45120
	s_waitcnt lgkmcnt(0)
	v_mfma_f32_32x32x16_bf16 v[0:15], v[20:23], v[28:31], v[0:15]
	ds_read_b128 v[28:31], v163 offset:62560
	ds_read_b128 v[64:67], v163 offset:45152
	s_waitcnt lgkmcnt(0)
	v_mfma_f32_32x32x16_bf16 v[0:15], v[28:31], v[64:67], v[0:15]
	ds_read_b128 v[72:75], v163 offset:62592
	ds_read_b128 v[64:67], v163 offset:45184
	s_waitcnt lgkmcnt(0)
	v_mfma_f32_32x32x16_bf16 v[0:15], v[72:75], v[64:67], v[0:15]
	ds_read_b128 v[76:79], v163 offset:62624
	ds_read_b128 v[64:67], v163 offset:45216
	s_waitcnt lgkmcnt(0)
	v_mfma_f32_32x32x16_bf16 v[0:15], v[76:79], v[64:67], v[0:15]
	ds_read_b128 v[80:83], v163 offset:62656
	ds_read_b128 v[64:67], v163 offset:45248
	s_waitcnt lgkmcnt(0)
	v_mfma_f32_32x32x16_bf16 v[0:15], v[80:83], v[64:67], v[0:15]
	ds_read_b128 v[84:87], v163 offset:62688
	ds_read_b128 v[64:67], v163 offset:45280
	ds_read_b128 v[170:173], v164 offset:45056
	ds_read_b128 v[174:177], v164 offset:45088
	ds_read_b128 v[178:181], v164 offset:45280
	s_waitcnt lgkmcnt(3)
	v_mfma_f32_32x32x16_bf16 v[0:15], v[84:87], v[64:67], v[0:15]
	s_nop 11
	v_cndmask_b32_e64 v64, v0, 0, s[78:79]
	v_cndmask_b32_e64 v0, v64, v0, s[76:77]
	v_cndmask_b32_e64 v1, 0, v1, s[76:77]
	v_cndmask_b32_e64 v2, v2, 0, s[74:75]
	v_cndmask_b32_e64 v3, v3, 0, s[46:47]
	v_cndmask_b32_e64 v4, v4, 0, s[44:45]
	v_cndmask_b32_e64 v5, v5, 0, s[42:43]
	v_cndmask_b32_e64 v6, v6, 0, s[38:39]
	v_cndmask_b32_e64 v7, v7, 0, s[36:37]
	v_cndmask_b32_e64 v8, v8, 0, s[40:41]
	v_cndmask_b32_e64 v9, v9, 0, s[18:19]
	v_cndmask_b32_e64 v10, v10, 0, s[16:17]
	v_cndmask_b32_e64 v11, v11, 0, s[14:15]
	v_cndmask_b32_e64 v12, v12, 0, s[12:13]
	v_cndmask_b32_e64 v13, v13, 0, s[30:31]
	v_cndmask_b32_e64 v14, v14, 0, s[24:25]
	v_cndmask_b32_e64 v15, v15, 0, s[0:1]
	v_cvt_pk_bf16_f32 v68, v0, v1
	v_cvt_pk_bf16_f32 v69, v2, v3
	v_cvt_pk_bf16_f32 v70, v4, v5
	v_cvt_pk_bf16_f32 v71, v6, v7
	v_cvt_pk_bf16_f32 v64, v8, v9
	v_cvt_pk_bf16_f32 v65, v10, v11
	v_cvt_pk_bf16_f32 v66, v12, v13
	v_cvt_pk_bf16_f32 v67, v14, v15
	s_waitcnt lgkmcnt(2)
	v_mfma_f32_32x32x16_bf16 v[0:15], v[16:19], v[170:173], 0
	ds_read_b128 v[16:19], v164 offset:45120
	s_waitcnt lgkmcnt(2)
	v_mfma_f32_32x32x16_bf16 v[0:15], v[24:27], v[174:177], v[0:15]
	ds_read_b128 v[24:27], v164 offset:45184
	s_waitcnt lgkmcnt(1)
	v_mfma_f32_32x32x16_bf16 v[0:15], v[20:23], v[16:19], v[0:15]
	ds_read_b128 v[20:23], v164 offset:45152
	s_waitcnt lgkmcnt(0)
	v_mfma_f32_32x32x16_bf16 v[0:15], v[28:31], v[20:23], v[0:15]
	ds_read_b128 v[28:31], v164 offset:45216
	v_mfma_f32_32x32x16_bf16 v[0:15], v[72:75], v[24:27], v[0:15]
	ds_read_b128 v[72:75], v164 offset:45248
	s_waitcnt lgkmcnt(1)
	v_mfma_f32_32x32x16_bf16 v[0:15], v[76:79], v[28:31], v[0:15]
	s_waitcnt lgkmcnt(0)
	v_mfma_f32_32x32x16_bf16 v[0:15], v[80:83], v[72:75], v[0:15]
	v_mfma_f32_32x32x16_bf16 v[0:15], v[84:87], v[178:181], v[0:15]
	ds_read_b128 v[84:87], v164 offset:62496
	s_nop 10
	v_cvt_pk_bf16_f32 v76, v0, v1
	v_cvt_pk_bf16_f32 v77, v2, v3
	ds_read_b128 v[0:3], v164 offset:62464
	v_cvt_pk_bf16_f32 v78, v4, v5
	v_cvt_pk_bf16_f32 v79, v6, v7
	v_cvt_pk_bf16_f32 v80, v8, v9
	v_cvt_pk_bf16_f32 v81, v10, v11
	v_cvt_pk_bf16_f32 v82, v12, v13
	v_cvt_pk_bf16_f32 v83, v14, v15
	s_waitcnt lgkmcnt(0)
	v_mfma_f32_32x32x16_bf16 v[0:15], v[0:3], v[170:173], 0
	v_mfma_f32_32x32x16_bf16 v[0:15], v[84:87], v[174:177], v[0:15]
	ds_read_b128 v[84:87], v164 offset:62528
	s_waitcnt lgkmcnt(0)
	v_mfma_f32_32x32x16_bf16 v[0:15], v[84:87], v[16:19], v[0:15]
	ds_read_b128 v[16:19], v164 offset:62560
	s_waitcnt lgkmcnt(0)
	v_mfma_f32_32x32x16_bf16 v[0:15], v[16:19], v[20:23], v[0:15]
	ds_read_b128 v[16:19], v164 offset:62592
	s_waitcnt lgkmcnt(0)
	v_mfma_f32_32x32x16_bf16 v[0:15], v[16:19], v[24:27], v[0:15]
	ds_read_b128 v[16:19], v164 offset:62624
	s_waitcnt lgkmcnt(0)
	v_mfma_f32_32x32x16_bf16 v[0:15], v[16:19], v[28:31], v[0:15]
	ds_read_b128 v[16:19], v164 offset:62656
	s_waitcnt lgkmcnt(0)
	v_mfma_f32_32x32x16_bf16 v[0:15], v[16:19], v[72:75], v[0:15]
	ds_read_b128 v[16:19], v164 offset:62688
	s_waitcnt lgkmcnt(0)
	v_mfma_f32_32x32x16_bf16 v[0:15], v[16:19], v[178:181], v[0:15]
	s_nop 11
	v_cndmask_b32_e64 v16, v0, 0, s[78:79]
	v_cndmask_b32_e64 v0, v16, v0, s[76:77]
	v_cndmask_b32_e64 v1, 0, v1, s[76:77]
	v_cndmask_b32_e64 v2, v2, 0, s[74:75]
	v_cndmask_b32_e64 v3, v3, 0, s[46:47]
	v_cvt_pk_bf16_f32 v84, v0, v1
	v_cvt_pk_bf16_f32 v85, v2, v3
	ds_read2_b64 v[0:3], v113 offset1:2
	ds_read2_b64 v[170:173], v113 offset0:4 offset1:6
	s_waitcnt lgkmcnt(1)
	s_waitcnt vmcnt(0)
	v_mfma_f32_32x32x16_bf16 v[16:31], v[60:63], v[0:3], 0
	ds_read2_b64 v[0:3], v115 offset1:2
	ds_read2_b64 v[174:177], v115 offset0:4 offset1:6
	v_cndmask_b32_e64 v4, v4, 0, s[44:45]
	v_cndmask_b32_e64 v5, v5, 0, s[42:43]
	v_cndmask_b32_e64 v6, v6, 0, s[38:39]
	v_cndmask_b32_e64 v7, v7, 0, s[36:37]
	v_cndmask_b32_e64 v8, v8, 0, s[40:41]
	v_cndmask_b32_e64 v9, v9, 0, s[18:19]
	v_cndmask_b32_e64 v10, v10, 0, s[16:17]
	v_cndmask_b32_e64 v11, v11, 0, s[14:15]
	v_cndmask_b32_e64 v12, v12, 0, s[12:13]
	v_cndmask_b32_e64 v13, v13, 0, s[30:31]
	v_cndmask_b32_e64 v14, v14, 0, s[24:25]
	v_cndmask_b32_e64 v15, v15, 0, s[0:1]
	v_cvt_pk_bf16_f32 v86, v4, v5
	v_cvt_pk_bf16_f32 v87, v6, v7
	v_cvt_pk_bf16_f32 v72, v8, v9
	v_cvt_pk_bf16_f32 v73, v10, v11
	v_cvt_pk_bf16_f32 v74, v12, v13
	v_cvt_pk_bf16_f32 v75, v14, v15
	s_waitcnt lgkmcnt(1)
	v_mfma_f32_32x32x16_bf16 v[0:15], v[60:63], v[0:3], 0
	v_mfma_f32_32x32x16_bf16 v[16:31], v[56:59], v[170:173], v[16:31]
	s_waitcnt lgkmcnt(0)
	v_mfma_f32_32x32x16_bf16 v[0:15], v[56:59], v[174:177], v[0:15]
	ds_read2_b64 v[56:59], v113 offset0:8 offset1:10
	s_waitcnt lgkmcnt(0)
	v_mfma_f32_32x32x16_bf16 v[16:31], v[52:55], v[56:59], v[16:31]
	ds_read2_b64 v[56:59], v115 offset0:8 offset1:10
	s_waitcnt lgkmcnt(0)
	v_mfma_f32_32x32x16_bf16 v[0:15], v[52:55], v[56:59], v[0:15]
	ds_read2_b64 v[52:55], v113 offset0:12 offset1:14
	s_waitcnt lgkmcnt(0)
	v_mfma_f32_32x32x16_bf16 v[16:31], v[48:51], v[52:55], v[16:31]
	ds_read2_b64 v[52:55], v115 offset0:12 offset1:14
	s_waitcnt lgkmcnt(0)
	v_mfma_f32_32x32x16_bf16 v[0:15], v[48:51], v[52:55], v[0:15]
	ds_read2_b64 v[48:51], v113 offset0:16 offset1:18
	s_waitcnt lgkmcnt(0)
	v_mfma_f32_32x32x16_bf16 v[16:31], v[44:47], v[48:51], v[16:31]
	ds_read2_b64 v[48:51], v115 offset0:16 offset1:18
	s_waitcnt lgkmcnt(0)
	v_mfma_f32_32x32x16_bf16 v[0:15], v[44:47], v[48:51], v[0:15]
	ds_read2_b64 v[44:47], v113 offset0:20 offset1:22
	s_waitcnt lgkmcnt(0)
	v_mfma_f32_32x32x16_bf16 v[16:31], v[40:43], v[44:47], v[16:31]
	ds_read2_b64 v[44:47], v115 offset0:20 offset1:22
	s_waitcnt lgkmcnt(0)
	v_mfma_f32_32x32x16_bf16 v[0:15], v[40:43], v[44:47], v[0:15]
	ds_read2_b64 v[40:43], v113 offset0:24 offset1:26
	s_waitcnt lgkmcnt(0)
	v_mfma_f32_32x32x16_bf16 v[16:31], v[36:39], v[40:43], v[16:31]
	ds_read2_b64 v[40:43], v115 offset0:24 offset1:26
	s_waitcnt lgkmcnt(0)
	v_mfma_f32_32x32x16_bf16 v[0:15], v[36:39], v[40:43], v[0:15]
	ds_read2_b64 v[36:39], v113 offset0:28 offset1:30
	s_waitcnt lgkmcnt(0)
	v_mfma_f32_32x32x16_bf16 v[16:31], v[32:35], v[36:39], v[16:31]
	ds_read2_b64 v[36:39], v115 offset0:28 offset1:30
	s_waitcnt lgkmcnt(0)
	v_mfma_f32_32x32x16_bf16 v[0:15], v[32:35], v[36:39], v[0:15]
	ds_read_b64_tr_b16 v[32:33], v167 offset:8192
	ds_read_b64_tr_b16 v[34:35], v167 offset:12800
	ds_read_b64_tr_b16 v[36:37], v167 offset:17408
	ds_read_b64_tr_b16 v[38:39], v167 offset:22016
	s_waitcnt lgkmcnt(2)
	v_mfma_f32_32x32x16_bf16 v[0:15], v[32:35], v[76:79], v[0:15]
	s_waitcnt lgkmcnt(0)
	v_mfma_f32_32x32x16_bf16 v[0:15], v[36:39], v[80:83], v[0:15]
	v_mfma_f32_32x32x16_bf16 v[16:31], v[32:35], v[68:71], v[16:31]
	ds_read_b64_tr_b16 v[32:33], v167 offset:26624
	ds_read_b64_tr_b16 v[34:35], v167 offset:31232
	s_waitcnt lgkmcnt(0)
	v_mfma_f32_32x32x16_bf16 v[0:15], v[32:35], v[84:87], v[0:15]
	ds_read_b64_tr_b16 v[32:33], v167 offset:35840
	ds_read_b64_tr_b16 v[34:35], v167 offset:40448
	v_mfma_f32_32x32x16_bf16 v[16:31], v[36:39], v[64:67], v[16:31]
	s_waitcnt lgkmcnt(0)
	v_mfma_f32_32x32x16_bf16 v[0:15], v[32:35], v[72:75], v[0:15]
	s_nop 9
	v_mul_f32_e32 v32, v17, v17
	v_fmac_f32_e32 v32, v16, v16
	v_fmac_f32_e32 v32, v18, v18
	v_fmac_f32_e32 v32, v19, v19
	v_fmac_f32_e32 v32, v20, v20
	v_fmac_f32_e32 v32, v21, v21
	v_fmac_f32_e32 v32, v22, v22
	v_mul_f32_e32 v33, v1, v1
	v_fmac_f32_e32 v33, v0, v0
	v_fmac_f32_e32 v33, v2, v2
	v_fmac_f32_e32 v33, v3, v3
	v_fmac_f32_e32 v33, v4, v4
	v_fmac_f32_e32 v33, v5, v5
	v_fmac_f32_e32 v33, v6, v6
	v_fmac_f32_e32 v32, v23, v23
	v_fmac_f32_e32 v33, v7, v7
	v_fmac_f32_e32 v32, v24, v24
	v_fmac_f32_e32 v33, v8, v8
	v_fmac_f32_e32 v32, v25, v25
	v_fmac_f32_e32 v33, v9, v9
	v_fmac_f32_e32 v32, v26, v26
	v_fmac_f32_e32 v33, v10, v10
	v_fmac_f32_e32 v32, v27, v27
	v_fmac_f32_e32 v33, v11, v11
	v_fmac_f32_e32 v32, v28, v28
	v_fmac_f32_e32 v33, v12, v12
	v_fmac_f32_e32 v32, v29, v29
	v_fmac_f32_e32 v33, v13, v13
	v_fmac_f32_e32 v32, v30, v30
	v_fmac_f32_e32 v33, v14, v14
	v_fmac_f32_e32 v32, v31, v31
	v_fmac_f32_e32 v33, v15, v15
	ds_bpermute_b32 v34, v148, v32
	ds_bpermute_b32 v35, v148, v33
	s_mov_b64 s[0:1], exec
	v_readlane_b32 s24, v245, 44
	v_readlane_b32 s25, v245, 45
	s_and_b64 s[24:25], s[0:1], s[24:25]
	s_mov_b64 exec, s[24:25]
	s_cbranch_execz .LBB0_130
	s_waitcnt lgkmcnt(0)
	v_add_f32_e32 v33, v33, v35
	v_add_f32_e32 v32, v32, v34
	ds_write2_b32 v168, v32, v33 offset1:32
	s_branch .LBB0_130
